# layer-0 MLP-in phase: workgroups 128-255 run their weight-conversion items before (not after) their GEMM units, de-synchronising the two groups' output-store bursts
# speedup vs baseline: 1.0045x; 1.0010x over previous
.LBB0_18:
	v_readlane_b32 s30, v251, 0
	s_ashr_i32 s2, s30, 31
	s_lshr_b32 s2, s2, 29
	s_add_i32 s8, s30, s2
	s_and_b32 s2, s8, -8
	s_sub_i32 s31, s30, s2
	s_lshl_b32 s2, s31, 5
	s_cmp_lt_i32 s31, 0
	s_mul_i32 s3, s31, 33
	s_movk_i32 s6, 0x5b
	s_cselect_b32 s7, s6, 0x5a
	s_cselect_b32 s6, s3, s2
	s_cmpk_eq_i32 s19, 0x100
	s_cselect_b64 s[2:3], -1, 0
	s_and_b64 s[2:3], s[2:3], exec
	s_cselect_b32 s48, 48, s19
	s_add_i32 s12, s30, 0xffffff30
	s_cmpk_eq_i32 s19, 0x100
	s_cselect_b64 s[2:3], -1, 0
	s_and_b64 s[10:11], s[2:3], exec
	s_cselect_b32 s33, s12, s30
	s_add_u32 s52, s26, 0xd340000
	s_addc_u32 s53, s27, 0
	s_add_u32 s10, s26, 0x28d3cc00
	s_addc_u32 s11, s27, 0
	v_writelane_b32 v251, s10, 3
	s_mul_i32 s7, s7, s31
	s_load_dwordx16 s[68:83], s[0:1], 0x40
	v_writelane_b32 v251, s11, 4
	s_add_u32 s10, s26, 0x28d3ca00
	s_addc_u32 s11, s27, 0
	v_writelane_b32 v251, s10, 5
	s_cmp_eq_u32 s9, 15
	s_mov_b32 s65, 0
	v_writelane_b32 v251, s11, 6
	s_cselect_b64 s[10:11], -1, 0
	v_writelane_b32 v251, s10, 7
	s_cmp_eq_u32 s9, 14
	s_mov_b32 s59, s46
	v_writelane_b32 v251, s11, 8
	s_cselect_b64 s[10:11], -1, 0
	v_writelane_b32 v251, s10, 9
	s_cmp_eq_u32 s9, 13
	v_mov_b32_e32 v193, 0
	v_writelane_b32 v251, s11, 10
	s_cselect_b64 s[10:11], -1, 0
	v_writelane_b32 v251, s10, 11
	s_cmp_eq_u32 s9, 12
	v_mov_b32_e32 v226, 1
	v_writelane_b32 v251, s11, 12
	s_cselect_b64 s[10:11], -1, 0
	v_writelane_b32 v251, s10, 13
	s_cmp_eq_u32 s9, 11
	v_mov_b32_e32 v227, 0x358637bd
	v_writelane_b32 v251, s11, 14
	s_cselect_b64 s[10:11], -1, 0
	v_writelane_b32 v251, s10, 15
	s_cmp_eq_u32 s9, 10
	v_mov_b32_e32 v228, 0x260
	v_writelane_b32 v251, s11, 16
	s_cselect_b64 s[10:11], -1, 0
	v_writelane_b32 v251, s10, 17
	s_cmp_eq_u32 s9, 9
	v_mov_b32_e32 v230, 3
	v_writelane_b32 v251, s11, 18
	s_cselect_b64 s[10:11], -1, 0
	v_writelane_b32 v251, s10, 19
	s_cmp_eq_u32 s9, 8
	v_mov_b32_e32 v231, 4
	v_writelane_b32 v251, s11, 20
	s_cselect_b64 s[10:11], -1, 0
	v_writelane_b32 v251, s10, 21
	s_cmp_eq_u32 s9, 7
	v_mov_b32_e32 v232, 6
	v_writelane_b32 v251, s11, 22
	s_cselect_b64 s[10:11], -1, 0
	v_writelane_b32 v251, s10, 23
	s_cmp_eq_u32 s9, 6
	v_mov_b32_e32 v233, 2
	v_writelane_b32 v251, s11, 24
	s_cselect_b64 s[10:11], -1, 0
	v_writelane_b32 v251, s10, 25
	s_cmp_eq_u32 s9, 5
	v_mov_b32_e32 v234, 5
	v_writelane_b32 v251, s11, 26
	s_cselect_b64 s[10:11], -1, 0
	v_writelane_b32 v251, s10, 27
	s_cmp_eq_u32 s9, 4
	v_mov_b32_e32 v235, 7
	v_writelane_b32 v251, s11, 28
	s_cselect_b64 s[10:11], -1, 0
	v_writelane_b32 v251, s10, 29
	s_cmp_eq_u32 s9, 3
	v_mov_b32_e32 v240, 0xef
	v_writelane_b32 v251, s11, 30
	s_cselect_b64 s[10:11], -1, 0
	v_writelane_b32 v251, s10, 31
	s_cmp_eq_u32 s9, 2
	v_mov_b32_e32 v241, 0x7ef
	v_writelane_b32 v251, s11, 32
	s_cselect_b64 s[10:11], -1, 0
	v_writelane_b32 v251, s10, 33
	s_cmp_eq_u32 s9, 1
	v_mov_b32_e32 v242, 0xff
	v_writelane_b32 v251, s11, 34
	s_cselect_b64 s[10:11], -1, 0
	v_writelane_b32 v251, s10, 35
	s_cmp_eq_u32 s9, 0
	v_mov_b32_e32 v243, 0x7ff
	v_writelane_b32 v251, s11, 36
	s_cselect_b64 s[10:11], -1, 0
	s_lshl_b32 s9, s9, 8
	s_add_u32 s4, s4, s9
	v_writelane_b32 v251, s10, 37
	s_addc_u32 s5, s5, 0
	v_mov_b32_e32 v244, 0xf8
	v_writelane_b32 v251, s11, 38
	s_add_u32 s10, s4, 0x1400
	s_addc_u32 s11, s5, 0
	v_writelane_b32 v251, s10, 39
	s_add_u32 s4, s4, 0x2400
	s_addc_u32 s5, s5, 0
	v_writelane_b32 v251, s11, 40
	v_writelane_b32 v251, s4, 41
	v_mov_b32_e32 v245, 0x7f8
	v_mov_b32_e32 v250, 0x42800000
	v_writelane_b32 v251, s5, 42
	s_add_u32 s4, s26, 0x28d3fc00
	s_addc_u32 s5, s27, 0
	v_writelane_b32 v251, s4, 43
	s_movk_i32 s66, 0x3000
	s_mov_b32 s96, 0x800000
	v_writelane_b32 v251, s5, 44
	s_add_u32 s4, s26, 0x28d3fd00
	s_addc_u32 s5, s27, 0
	v_writelane_b32 v251, s4, 45
	s_movk_i32 s97, 0x104
	s_nop 0
	v_writelane_b32 v251, s5, 46
	s_add_u32 s4, s26, 0x2d00000
	v_writelane_b32 v251, s4, 47
	s_addc_u32 s4, s27, 0
	v_writelane_b32 v251, s4, 48
	s_add_u32 s4, s26, 0x2800000
	s_addc_u32 s5, s27, 0
	v_writelane_b32 v251, s4, 49
	s_cmp_lt_i32 s30, 64
	s_nop 0
	v_writelane_b32 v251, s5, 50
	s_cselect_b64 s[4:5], -1, 0
	v_cndmask_b32_e64 v225, 0, 1, s[4:5]
	s_and_b64 s[4:5], s[4:5], exec
	s_cselect_b32 s4, s19, 0
	s_add_i32 s14, s30, s4
	s_add_u32 s4, s26, 0x3e00000
	v_writelane_b32 v251, s4, 51
	s_addc_u32 s4, s27, 0
	v_writelane_b32 v251, s4, 52
	s_add_u32 s4, s26, 0x4200000
	s_addc_u32 s5, s27, 0
	s_add_u32 s34, s26, 0xdc3c800
	s_addc_u32 s35, s27, 0
	s_lshl_b32 s36, s30, 3
	s_lshl_b32 s50, s19, 3
	v_writelane_b32 v251, s4, 53
	s_cmpk_lt_i32 s30, 0x1cd1
	s_nop 0
	v_writelane_b32 v251, s5, 54
	s_cselect_b64 s[4:5], -1, 0
	v_writelane_b32 v251, s4, 55
	s_nop 1
	v_writelane_b32 v251, s5, 56
	s_add_u32 s4, s26, 0xd43c000
	s_addc_u32 s5, s27, 0
	v_writelane_b32 v251, s4, 57
	s_nop 1
	v_writelane_b32 v251, s5, 58
	s_add_u32 s4, s26, 0xd3b8000
	s_addc_u32 s5, s27, 0
	v_writelane_b32 v251, s4, 59
	s_nop 1
	v_writelane_b32 v251, s5, 60
	s_add_u32 s4, s26, 0xd3bc000
	s_addc_u32 s5, s27, 0
	s_add_u32 s16, s26, 0xd300000
	v_writelane_b32 v251, s4, 61
	s_addc_u32 s17, s27, 0
	s_nop 0
	v_writelane_b32 v251, s5, 62
	s_add_u32 s4, s26, 0x8300000
	v_writelane_b32 v251, s4, 63
	s_addc_u32 s4, s27, 0
	v_writelane_b32 v252, s4, 0
	s_add_u32 s4, s26, 0x4300000
	v_writelane_b32 v252, s4, 1
	s_addc_u32 s4, s27, 0
	v_writelane_b32 v252, s4, 2
	s_add_u32 s4, s26, 0x2e00000
	v_writelane_b32 v252, s4, 3
	s_addc_u32 s4, s27, 0
	v_writelane_b32 v252, s4, 4
	s_add_u32 s4, s26, 0xd43c800
	v_writelane_b32 v252, s4, 5
	s_addc_u32 s4, s27, 0
	s_add_u32 s38, s26, 0x1fd3c800
	s_addc_u32 s39, s27, 0
	v_writelane_b32 v252, s4, 6
	s_add_u32 s4, s26, 0x1753c800
	s_addc_u32 s5, s27, 0
	v_writelane_b32 v252, s4, 7
	s_nop 1
	v_writelane_b32 v252, s5, 8
	s_add_u32 s4, s26, 0x1bd3c800
	s_addc_u32 s5, s27, 0
	v_writelane_b32 v252, s4, 9
	s_cmpk_lt_i32 s30, 0x100
	s_nop 0
	v_writelane_b32 v252, s5, 10
	s_cselect_b64 s[4:5], -1, 0
	v_writelane_b32 v252, s4, 11
	s_and_b32 s10, s30, 7
	s_bfe_u32 s13, s30, 0x30003
	v_writelane_b32 v252, s5, 12
	s_add_i32 s4, s30, 0x700
	s_bfe_u32 s4, s4, 0x50006
	s_or_b32 s11, s4, 32
	s_add_i32 s4, s10, 1
	v_writelane_b32 v252, s4, 13
	s_lshl_b32 s4, s11, 22
	s_add_u32 s4, s38, s4
	s_addc_u32 s5, s39, 0
	s_lshl_b32 s9, s10, 11
	s_add_u32 s4, s4, s9
	v_writelane_b32 v252, s9, 14
	s_addc_u32 s5, s5, 0
	v_writelane_b32 v252, s4, 15
	s_ashr_i32 s15, s8, 3
	s_nop 0
	v_writelane_b32 v252, s5, 16
	s_lshl_b32 s4, s13, 22
	s_cmpk_gt_i32 s30, 0x7f
	v_writelane_b32 v252, s4, 17
	s_cselect_b64 s[4:5], -1, 0
	s_and_b64 s[4:5], s[4:5], s[2:3]
	v_writelane_b32 v252, s4, 18
	s_cmpk_lg_i32 s19, 0x100
	s_nop 0
	v_writelane_b32 v252, s5, 19
	s_cselect_b64 s[4:5], -1, 0
	s_cmpk_lt_i32 s30, 0x800
	s_cselect_b64 s[8:9], -1, 0
	s_add_u32 s55, s22, 0x4000000
	s_addc_u32 s58, s23, 0
	s_add_u32 s62, s26, 0xa300000
	s_addc_u32 s63, s27, 0
	s_add_u32 s12, s20, 0x4000000
	v_writelane_b32 v252, s12, 20
	s_addc_u32 s12, s21, 0
	s_add_u32 s28, s26, 0x6300000
	v_writelane_b32 v252, s12, 21
	s_addc_u32 s29, s27, 0
	v_writelane_b32 v252, s28, 22
	s_cmpk_lt_i32 s30, 0x680
	s_nop 0
	v_writelane_b32 v252, s29, 23
	s_cselect_b64 s[28:29], -1, 0
	v_writelane_b32 v252, s28, 24
	s_nop 1
	v_writelane_b32 v252, s29, 25
	s_add_u32 s28, s26, 0x28d40800
	s_addc_u32 s29, s27, 0
	v_writelane_b32 v252, s28, 26
	s_add_u32 s37, s26, 0x1513c800
	s_addc_u32 s40, s27, 0
	v_writelane_b32 v252, s29, 27
	v_writelane_b32 v252, s11, 28
	s_lshl_b32 s11, s11, 20
	s_add_u32 s11, s37, s11
	s_addc_u32 s12, s40, 0
	s_lshl_b32 s10, s10, 9
	v_writelane_b32 v252, s10, 29
	s_add_u32 s10, s11, s10
	s_addc_u32 s11, s12, 0
	v_writelane_b32 v252, s10, 30
	s_nop 1
	v_writelane_b32 v252, s11, 31
	v_writelane_b32 v252, s13, 32
	s_lshl_b32 s10, s13, 20
	v_writelane_b32 v252, s10, 33
	s_add_u32 s10, s26, 0xd43c040
	v_writelane_b32 v252, s10, 34
	s_addc_u32 s10, s27, 0
	v_writelane_b32 v252, s10, 35
	s_add_u32 s10, s26, 0x1103c800
	s_addc_u32 s11, s27, 0
	v_writelane_b32 v252, s10, 36
	s_nop 1
	v_writelane_b32 v252, s11, 37
	s_add_u32 s10, s26, 0xd320000
	s_addc_u32 s11, s27, 0
	v_writelane_b32 v252, s10, 38
	s_nop 1
	v_writelane_b32 v252, s11, 39
	s_add_u32 s10, s26, 0xd300080
	s_addc_u32 s11, s27, 0
	v_writelane_b32 v252, s10, 40
	s_nop 1
	v_writelane_b32 v252, s11, 41
	s_add_u32 s10, s26, 0x1123c800
	s_addc_u32 s11, s27, 0
	v_writelane_b32 v252, s10, 42
	s_nop 1
	v_writelane_b32 v252, s11, 43
	s_add_u32 s10, s26, 0x11b3c800
	s_addc_u32 s11, s27, 0
	s_add_u32 s56, s26, 0x12d3c800
	s_addc_u32 s57, s27, 0
	s_add_u32 s44, s26, 0x13f3c800
	v_writelane_b32 v252, s10, 44
	s_addc_u32 s45, s27, 0
	s_nop 0
	v_writelane_b32 v252, s11, 45
	s_add_u32 s10, s26, 0xd43c400
	v_writelane_b32 v252, s10, 46
	s_addc_u32 s10, s27, 0
	v_writelane_b32 v252, s10, 47
	s_add_u32 s10, s26, 0x1003c800
	s_addc_u32 s11, s27, 0
	v_writelane_b32 v252, s10, 48
	s_cmpk_lt_i32 s30, 0x2d0
	s_nop 0
	v_writelane_b32 v252, s11, 49
	s_cselect_b64 s[10:11], -1, 0
	v_writelane_b32 v252, s10, 50
	s_add_i32 s7, s7, s15
	s_nop 0
	v_writelane_b32 v252, s11, 51
	s_mul_hi_i32 s10, s7, 0xb60b60b7
	s_add_i32 s10, s10, s7
	s_lshr_b32 s11, s10, 31
	s_ashr_i32 s10, s10, 6
	s_add_i32 s18, s10, s11
	s_mul_i32 s10, s18, 0xffffffa6
	s_add_i32 s28, s10, s7
	s_mul_i32 s7, s18, 54
	s_add_i32 s29, s7, 0xfc
	s_cmpk_gt_i32 s30, 0xcf
	s_cselect_b64 s[10:11], -1, 0
	s_or_b64 s[10:11], s[10:11], s[4:5]
	s_cmpk_lt_i32 s33, 0x200
	s_cselect_b64 s[12:13], -1, 0
	s_waitcnt lgkmcnt(0)
	s_add_u32 s42, s72, 0x2400000
	s_addc_u32 s43, s73, 0
	v_writelane_b32 v252, s42, 52
	s_mul_i32 s18, s18, 36
	s_nop 0
	v_writelane_b32 v252, s43, 53
	s_add_u32 s42, s26, 0x1400000
	s_addc_u32 s43, s27, 0
	s_sub_i32 s7, s14, 64
	s_cmpk_gt_i32 s19, 0x5f
	s_cselect_b32 s7, s7, s30
	v_writelane_b32 v252, s42, 54
	s_cmp_lt_i32 s7, 32
	s_nop 0
	v_writelane_b32 v252, s43, 55
	s_cselect_b64 s[42:43], -1, 0
	s_add_i32 s6, s6, s15
	v_writelane_b32 v252, s7, 56
	s_ashr_i32 s7, s6, 31
	s_lshr_b32 s7, s7, 26
	s_add_i32 s7, s6, s7
	s_and_b32 s14, s7, 0xffc0
	s_sub_i32 s6, s6, s14
	s_bfe_i32 s14, s6, 0x80000
	v_writelane_b32 v252, s42, 57
	s_bfe_u32 s14, s14, 0x3000c
	s_add_i32 s14, s6, s14
	v_writelane_b32 v252, s43, 58
	v_writelane_b32 v252, s15, 59
	s_and_b32 s15, s14, 0xf8
	s_sub_i32 s6, s6, s15
	s_ashr_i32 s7, s7, 6
	s_lshl_b32 s7, s7, 3
	s_bfe_i32 s14, s14, 0x80000
	s_sext_i32_i8 s6, s6
	s_sext_i32_i16 s14, s14
	s_add_i32 s42, s7, s6
	v_writelane_b32 v252, s31, 60
	s_lshr_b32 s6, s31, 31
	s_ashr_i32 s43, s42, 31
	v_writelane_b32 v252, s6, 61
	s_ashr_i32 s6, s14, 3
	v_writelane_b32 v252, s6, 62
	s_lshr_b32 s6, s14, 3
	s_lshl_b64 s[14:15], s[42:43], 22
	s_add_u32 s14, s38, s14
	v_writelane_b32 v252, s38, 63
	s_addc_u32 s15, s39, s15
	s_and_b64 s[4:5], s[4:5], s[8:9]
	v_writelane_b32 v253, s39, 0
	v_writelane_b32 v253, s14, 1
	s_nop 1
	v_writelane_b32 v253, s15, 2
	v_writelane_b32 v253, s4, 3
	s_nop 1
	v_writelane_b32 v253, s5, 4
	s_bfe_i64 s[4:5], s[6:7], 0x100000
	s_lshl_b64 s[6:7], s[4:5], 22
	v_writelane_b32 v253, s6, 5
	s_nop 1
	v_writelane_b32 v253, s7, 6
	s_mov_b32 s6, s42
	v_writelane_b32 v253, s6, 7
	s_nop 1
	v_writelane_b32 v253, s7, 8
	s_lshl_b64 s[6:7], s[42:43], 20
	v_writelane_b32 v253, s37, 9
	s_add_u32 s6, s37, s6
	v_writelane_b32 v253, s40, 10
	s_addc_u32 s7, s40, s7
	v_writelane_b32 v253, s6, 11
	s_lshl_b64 s[4:5], s[4:5], 20
	s_cmp_lt_i32 s28, 36
	v_writelane_b32 v253, s7, 12
	v_writelane_b32 v253, s4, 13
	s_mov_b32 s42, 0x400000
	s_mov_b32 s43, 0xc00000
	v_writelane_b32 v253, s5, 14
	s_cselect_b32 s4, s18, s29
	s_add_i32 s4, s28, s4
	s_cmpk_gt_i32 s4, 0x11f
	s_cselect_b64 s[6:7], -1, 0
	v_writelane_b32 v253, s6, 15
	s_add_i32 s5, s4, 0xfffffee0
	s_mov_b32 s18, 0x3f3504f3
	v_writelane_b32 v253, s7, 16
	s_mul_hi_u32 s6, s5, 0xaaaaaaab
	s_lshr_b32 s6, s6, 6
	s_mul_i32 s7, s6, 0x60
	s_sub_i32 s8, s5, s7
	s_mul_hi_i32 s5, s4, 0x38e38e39
	s_lshr_b32 s7, s5, 31
	s_ashr_i32 s5, s5, 6
	s_add_i32 s5, s5, s7
	s_mul_i32 s7, s5, 0x120
	s_sub_i32 s4, s4, s7
	s_bfe_u32 s7, s4, 0x3001c
	s_add_i32 s7, s4, s7
	s_and_b32 s9, s7, 0xfff8
	s_sub_i32 s4, s4, s9
	s_lshl_b32 s9, s6, 3
	s_sub_i32 s6, 36, s9
	s_min_i32 s14, s6, 8
	s_lshl_b32 s5, s5, 3
	s_sext_i32_i16 s6, s7
	s_sext_i32_i16 s4, s4
	s_add_i32 s28, s5, s4
	s_ashr_i32 s4, s6, 3
	v_writelane_b32 v253, s4, 17
	s_lshr_b32 s4, s6, 3
	s_cmp_gt_i32 s28, 3
	s_cselect_b64 s[6:7], -1, 0
	v_cndmask_b32_e64 v0, 0, 1, s[6:7]
	s_mov_b32 s6, s28
	s_ashr_i32 s29, s28, 31
	s_bfe_i64 s[4:5], s[4:5], 0x100000
	v_writelane_b32 v253, s6, 18
	s_lshl_b64 s[4:5], s[4:5], 20
	s_nop 0
	v_writelane_b32 v253, s7, 19
	s_lshl_b64 s[6:7], s[28:29], 20
	v_writelane_b32 v253, s6, 20
	s_add_u32 s4, s34, s4
	s_addc_u32 s5, s35, s5
	v_writelane_b32 v253, s7, 21
	v_writelane_b32 v253, s4, 22
	s_nop 1
	v_writelane_b32 v253, s5, 23
	s_add_i32 s4, s30, 0xfffffd30
	s_cmp_gt_u32 s4, 0xfffffdff
	s_cselect_b64 s[4:5], -1, 0
	s_and_b64 s[2:3], s[4:5], s[2:3]
	v_writelane_b32 v253, s2, 24
	s_nop 1
	v_writelane_b32 v253, s3, 25
	s_and_b64 s[2:3], s[10:11], s[12:13]
	v_writelane_b32 v253, s2, 26
	s_nop 1
	v_writelane_b32 v253, s3, 27
	s_abs_i32 s2, s14
	v_cvt_f32_u32_e32 v1, s2
	s_sub_i32 s3, 0, s2
	v_rcp_iflag_f32_e32 v1, v1
	s_nop 0
	v_mul_f32_e32 v1, 0x4f7ffffe, v1
	v_cvt_u32_f32_e32 v1, v1
	s_nop 0
	v_readfirstlane_b32 s4, v1
	s_mul_i32 s3, s3, s4
	s_mul_hi_u32 s3, s4, s3
	s_add_i32 s4, s4, s3
	s_abs_i32 s3, s8
	s_mul_hi_u32 s4, s3, s4
	s_mul_i32 s5, s4, s2
	s_sub_i32 s3, s3, s5
	s_xor_b32 s5, s8, s14
	s_ashr_i32 s5, s5, 31
	s_add_i32 s6, s4, 1
	s_sub_i32 s7, s3, s2
	s_cmp_ge_u32 s3, s2
	s_cselect_b32 s4, s6, s4
	s_cselect_b32 s3, s7, s3
	s_add_i32 s6, s4, 1
	s_cmp_ge_u32 s3, s2
	s_cselect_b32 s2, s6, s4
	s_xor_b32 s2, s2, s5
	s_sub_i32 s4, s2, s5
	s_mul_i32 s2, s4, s14
	s_sub_i32 s2, s8, s2
	s_add_i32 s6, s2, s9
	s_ashr_i32 s2, s4, 2
	s_add_i32 s2, s2, 2
	v_writelane_b32 v253, s2, 28
	s_mov_b32 s2, s6
	s_mov_b32 s7, s65
	v_writelane_b32 v253, s2, 29
	v_mbcnt_lo_u32_b32 v1, -1, 0
	v_mbcnt_hi_u32_b32 v229, -1, v1
	v_writelane_b32 v253, s3, 30
	s_lshl_b64 s[2:3], s[6:7], 20
	s_add_u32 s2, s34, s2
	v_writelane_b32 v253, s34, 31
	s_addc_u32 s3, s35, s3
	s_movk_i32 s7, 0x1200
	v_writelane_b32 v253, s35, 32
	v_writelane_b32 v253, s2, 33
	s_mov_b32 s8, 0xbf3504f3
	s_nop 0
	v_writelane_b32 v253, s3, 34
	s_lshl_b32 s2, s4, 8
	s_ashr_i32 s3, s2, 31
	s_lshl_b64 s[2:3], s[2:3], 12
	v_writelane_b32 v253, s4, 35
	s_add_u32 s2, s2, 0x800000
	v_writelane_b32 v253, s2, 36
	s_addc_u32 s2, s3, 0
	v_writelane_b32 v253, s2, 37
	s_add_u32 s2, s26, 0x3e20080
	v_writelane_b32 v253, s2, 38
	s_addc_u32 s2, s27, 0
	s_ashr_i32 s51, s50, 31
	v_writelane_b32 v253, s2, 39
	s_lshl_b64 s[2:3], s[50:51], 12
	s_add_u32 s4, s74, 0x400000
	v_writelane_b32 v253, s68, 40
	s_addc_u32 s5, s75, 0
	s_add_i32 s6, 0, 0x20000
	v_writelane_b32 v253, s69, 41
	v_writelane_b32 v253, s70, 42
	v_writelane_b32 v253, s71, 43
	v_writelane_b32 v253, s72, 44
	v_writelane_b32 v253, s73, 45
	v_writelane_b32 v253, s74, 46
	v_writelane_b32 v253, s75, 47
	v_writelane_b32 v253, s76, 48
	v_writelane_b32 v253, s77, 49
	v_writelane_b32 v253, s78, 50
	v_writelane_b32 v253, s79, 51
	v_writelane_b32 v253, s80, 52
	v_writelane_b32 v253, s81, 53
	v_writelane_b32 v253, s82, 54
	v_writelane_b32 v253, s83, 55
	v_writelane_b32 v253, s4, 56
	s_mov_b64 s[76:77], s[2:3]
	v_readfirstlane_b32 s2, v0
	v_writelane_b32 v253, s5, 57
	s_lshl_b32 s3, s19, 6
	v_writelane_b32 v253, s2, 58
	s_add_i32 s2, s30, 0xffffe350
	v_writelane_b32 v253, s2, 59
	s_add_i32 s2, s30, 0xffffe3d0
	v_writelane_b32 v253, s2, 60
	v_writelane_b32 v253, s3, 61
	s_lshl_b32 s4, s19, 1
	s_lshl_b32 s2, s30, 6
	v_writelane_b32 v253, s4, 62
	s_add_i32 s4, s36, 0xfffffc00
	v_writelane_b32 v253, s4, 63
	s_add_i32 s4, s2, 0xffffe000
	s_lshl_b32 s3, s30, 1
	v_writelane_b32 v254, s4, 0
	v_writelane_b32 v254, s3, 1
	s_addk_i32 s3, 0xff00
	v_writelane_b32 v254, s3, 2
	s_add_i32 s3, s30, 0xffffff00
	v_writelane_b32 v254, s3, 3
	s_add_i32 s3, s30, 0x500
	v_writelane_b32 v254, s3, 4
	v_writelane_b32 v254, s36, 5
	s_add_i32 s3, s36, 0x2980
	v_writelane_b32 v254, s3, 6
	v_writelane_b32 v254, s2, 7
	s_add_i32 s2, s2, 0x14c00
	v_writelane_b32 v254, s2, 8
	s_lshl_b32 s2, s33, 2
	v_writelane_b32 v254, s2, 9
	s_lshl_b32 s2, s48, 2
	v_writelane_b32 v254, s2, 10
	v_writelane_b32 v254, s33, 11
	s_lshl_b32 s2, s33, 6
	v_writelane_b32 v254, s2, 12
	s_lshl_b32 s2, s48, 6
	v_writelane_b32 v254, s2, 13
	s_add_i32 s2, 0, 0x20010
	s_load_dwordx16 s[80:95], s[0:1], 0x0
	v_writelane_b32 v254, s2, 14
	s_add_i32 s2, 0, 0x20014
	v_writelane_b32 v254, s2, 15
	s_mov_b32 s2, 0xbf6c835e
	v_writelane_b32 v254, s2, 16
	s_movk_i32 s33, 0x2000
	s_movk_i32 s30, 0x1000
	v_writelane_b32 v254, s3, 17
	s_waitcnt lgkmcnt(0)
	v_writelane_b32 v254, s80, 18
	s_mov_b64 s[72:73], 0x80
	s_mov_b64 s[78:79], 0x2000
	v_writelane_b32 v254, s81, 19
	v_writelane_b32 v254, s82, 20
	v_writelane_b32 v254, s83, 21
	v_writelane_b32 v254, s84, 22
	v_writelane_b32 v254, s85, 23
	v_writelane_b32 v254, s86, 24
	v_writelane_b32 v254, s87, 25
	v_writelane_b32 v254, s88, 26
	v_writelane_b32 v254, s89, 27
	v_writelane_b32 v254, s90, 28
	v_writelane_b32 v254, s91, 29
	v_writelane_b32 v254, s92, 30
	v_writelane_b32 v254, s93, 31
	v_writelane_b32 v254, s94, 32
	v_writelane_b32 v254, s95, 33
	s_load_dwordx16 s[80:95], s[0:1], 0x80
	s_mov_b32 s70, 0x3ec3ef15
	s_mov_b32 s68, 0x3f6c835e
	s_waitcnt lgkmcnt(0)
	v_writelane_b32 v254, s80, 34
	s_nop 1
	v_writelane_b32 v254, s81, 35
	v_writelane_b32 v254, s82, 36
	v_writelane_b32 v254, s83, 37
	v_writelane_b32 v254, s84, 38
	v_writelane_b32 v254, s85, 39
	v_writelane_b32 v254, s86, 40
	v_writelane_b32 v254, s87, 41
	v_writelane_b32 v254, s88, 42
	v_writelane_b32 v254, s89, 43
	v_writelane_b32 v254, s90, 44
	v_writelane_b32 v254, s91, 45
	v_writelane_b32 v254, s92, 46
	v_writelane_b32 v254, s93, 47
	v_writelane_b32 v254, s94, 48
	v_writelane_b32 v254, s95, 49
	v_writelane_b32 v254, s46, 50
	s_nop 1
	v_writelane_b32 v254, s47, 51
	v_writelane_b32 v254, s48, 52
	v_writelane_b32 v254, s52, 53
	s_nop 1
	v_writelane_b32 v254, s53, 54
	v_writelane_b32 v254, s50, 55
	s_nop 1
	v_writelane_b32 v254, s51, 56
	v_writelane_b32 v254, s55, 57
	v_writelane_b32 v254, s58, 58
	v_writelane_b32 v254, s62, 59
	s_nop 1
	v_writelane_b32 v254, s63, 60
	v_writelane_b32 v254, s56, 61
	s_nop 1
	v_writelane_b32 v254, s57, 62
	v_writelane_b32 v254, s76, 63
	s_nop 1
	v_writelane_b32 v255, s77, 0
	v_writelane_b32 v255, 0, 42
	s_branch .LBB0_21

.LBB0_249:
	v_readlane_b32 s98, v255, 1
	s_cmp_lg_u32 s98, 6
	s_cbranch_scc1 .Lpc_gemm
	v_readlane_b32 s98, v251, 0
	s_cmp_lt_u32 s98, 128
	s_cbranch_scc1 .Lpc_gemm
	v_readlane_b32 s98, v255, 42
	s_cmp_lg_u32 s98, 0
	s_cbranch_scc1 .Lpc_gemm
	s_mov_b32 s98, 1
	s_nop 1
	v_writelane_b32 v255, s98, 42
	v_writelane_b32 v255, s0, 43
	v_writelane_b32 v255, s1, 44
	v_readlane_b32 s2, v254, 3
	v_readlane_b32 s3, v254, 2
	v_readlane_b32 s4, v254, 0
	v_readlane_b32 s5, v253, 63
	v_readlane_b32 s62, v254, 59
	v_readlane_b32 s55, v254, 57
	v_readlane_b32 s58, v254, 58
	v_readlane_b32 s63, v254, 60
	s_nop 3
	s_branch .LBB0_286

.LBB0_264:
	s_andn2_b64 vcc, exec, s[0:1]
	s_cbranch_vccnz .LBB0_266
	v_readlane_b32 s0, v252, 24
	v_readlane_b32 s1, v252, 25
	s_andn2_b64 vcc, exec, s[0:1]
	v_readlane_b32 s2, v254, 3
	v_readlane_b32 s3, v254, 2
	v_readlane_b32 s4, v254, 0
	v_readlane_b32 s5, v253, 63
	v_readlane_b32 s98, v255, 42
	s_cmp_lg_u32 s98, 2
	s_cbranch_scc1 .Lpc_noskip
	v_writelane_b32 v255, 0, 42
	s_branch .LBB0_266
.Lpc_noskip:
	s_cbranch_vccz .LBB0_286

.Lpc_convdone:
	v_readlane_b32 s98, v255, 42
	s_cmp_lg_u32 s98, 1
	s_cbranch_scc1 .LBB0_266
	s_mov_b32 s98, 2
	s_nop 1
	v_writelane_b32 v255, s98, 42
	v_readlane_b32 s0, v255, 43
	v_readlane_b32 s1, v255, 44
	s_nop 3
	s_branch .Lpc_gemm
